# v13: + rpb table load overlapped with NA Q/K/V prologue loads; phase 1: waves 4-7 run norm before Wf-fold (waves 0-3 fold first) so LDS/VALU-bound and memory-bound parts overlap per SIMD
# speedup vs baseline: 1.0328x; 1.0048x over previous
.LBB0_174:
	s_or_b64 exec, exec, s[4:5]
	v_readfirstlane_b32 s12, v195
	s_nop 3
	s_cmp_lt_u32 s12, 0x100
	s_cbranch_scc1 .Lp1_fold
	s_mov_b32 s12, 1
	s_nop 0
	v_writelane_b32 v255, s12, 62
	s_branch .LBB0_179
.Lp1_fold:
	s_mov_b32 s12, 0
	s_nop 0
	v_writelane_b32 v255, s12, 62
.Lp1_fold_entry:
	s_ashr_i32 s18, s18, 6
	s_cmpk_gt_i32 s18, 0x7ff
	s_cbranch_scc1 .LBB0_179
	v_lshlrev_b32_e32 v0, 7, v4
	v_and_b32_e32 v0, 0xffffe000, v0
	s_load_dwordx2 s[14:15], s[8:9], 0x48
	v_add_u32_e32 v146, 0, v0
	v_and_b32_e32 v0, 63, v4
	s_ashr_i32 s19, s66, 6
	v_lshlrev_b32_e32 v128, 2, v0
	v_lshrrev_b32_e32 v2, 1, v4
	v_mov_b32_e32 v129, 0
	v_lshlrev_b32_e32 v0, 4, v0
	v_and_b32_e32 v1, 16, v128
	v_and_b32_e32 v2, 12, v2
	v_and_b32_e32 v3, 35, v4
	s_waitcnt lgkmcnt(0)
	s_add_u32 s20, s6, 0x2fe000
	s_mov_b32 s13, 0
	v_or3_b32 v147, v3, v2, v1
	s_addc_u32 s21, s7, 0
	v_lshl_add_u64 v[130:131], s[6:7], 0, v[128:129]
	v_lshlrev_b32_e32 v132, 2, v128
	v_mov_b32_e32 v133, v129
	s_movk_i32 s22, 0x2000
	s_mov_b32 s23, 0x8000
	s_mov_b32 s24, 0xe000
	s_mov_b32 s25, 0x14000
	s_mov_b32 s26, 0x1a000
	s_mov_b32 s27, 0x20000
	s_mov_b32 s28, 0x26000
	s_mov_b32 s29, 0x2c000
	v_add_u32_e32 v148, v146, v0
	s_mov_b32 s30, 0x1ff000
	s_mov_b32 s31, 0x200000
	s_mov_b32 s34, 0x201000

.LBB0_179:
	v_readlane_b32 s4, v255, 62
	s_nop 3
	s_cmp_eq_u32 s4, 2
	s_cbranch_scc1 .LBB0_193
	v_readlane_b32 s4, v253, 2
	v_readlane_b32 s5, v253, 3
	s_andn2_b64 vcc, exec, s[4:5]
	s_cbranch_vccnz .Lp1_after_norm
	v_mov_b32_e32 v0, v195
	s_mul_i32 s4, s2, s89
	s_nop 0
	v_add_u32_e32 v1, s4, v0
	s_nop 0
	v_readfirstlane_b32 s4, v1
	s_cmp_gt_u32 s4, 0xbffff
	s_cbranch_scc1 .Lp1_after_norm
	v_mbcnt_lo_u32_b32 v1, -1, 0
	v_mbcnt_hi_u32_b32 v1, -1, v1
	v_and_b32_e32 v2, 64, v1
	v_add_u32_e32 v2, 64, v2
	v_xor_b32_e32 v3, 32, v1
	v_cmp_lt_i32_e32 vcc, v3, v2
	s_lshr_b32 s17, s66, 6
	s_waitcnt lgkmcnt(0)
	s_add_u32 s39, s6, 0x1e0000
	v_cndmask_b32_e32 v3, v1, v3, vcc
	v_lshlrev_b32_e32 v103, 2, v3
	v_xor_b32_e32 v3, 16, v1
	v_cmp_lt_i32_e32 vcc, v3, v2
	s_addc_u32 s40, s7, 0
	s_lshr_b32 s41, s4, 6
	v_cndmask_b32_e32 v3, v1, v3, vcc
	v_lshlrev_b32_e32 v108, 2, v3
	v_xor_b32_e32 v3, 8, v1
	v_cmp_lt_i32_e32 vcc, v3, v2
	s_load_dwordx2 s[4:5], s[8:9], 0x30
	v_lshlrev_b32_e32 v0, 2, v0
	v_cndmask_b32_e32 v3, v1, v3, vcc
	v_lshlrev_b32_e32 v109, 2, v3
	v_xor_b32_e32 v3, 4, v1
	v_cmp_lt_i32_e32 vcc, v3, v2
	v_and_b32_e32 v0, 0xfc, v0
	v_mov_b32_e32 v97, 0
	v_cndmask_b32_e32 v3, v1, v3, vcc
	v_lshlrev_b32_e32 v110, 2, v3
	v_xor_b32_e32 v3, 2, v1
	v_cmp_lt_i32_e32 vcc, v3, v2
	v_lshlrev_b32_e32 v96, 2, v0
	s_waitcnt lgkmcnt(0)
	v_lshl_add_u64 v[98:99], s[4:5], 0, v[96:97]
	v_cndmask_b32_e32 v3, v1, v3, vcc
	v_lshlrev_b32_e32 v111, 2, v3
	v_xor_b32_e32 v3, 1, v1
	v_cmp_lt_i32_e32 vcc, v3, v2
	v_lshlrev_b32_e32 v96, 1, v0
	v_or_b32_e32 v2, 0x100, v0
	v_cndmask_b32_e32 v1, v1, v3, vcc
	v_or_b32_e32 v4, 0x200, v0
	v_or_b32_e32 v6, 0x300, v0
	v_lshl_add_u64 v[8:9], s[6:7], 0, v[96:97]
	s_mov_b64 s[4:5], 0x39fe000
	s_mul_i32 s38, s17, 6
	s_mov_b32 s13, 0
	v_lshlrev_b32_e32 v112, 2, v1
	v_lshl_add_u64 v[100:101], v[8:9], 0, s[4:5]
	s_lshl_b32 s14, s41, 10
	s_mul_i32 s42, s17, 0x1800
	s_lshl_b32 s43, s17, 1
	s_lshl_b32 s44, s17, 11
	s_mul_i32 s45, s17, 3
	s_mul_i32 s46, s17, 0xc00
	s_lshl_b32 s47, s17, 2
	s_lshl_b32 s48, s17, 12
	s_mul_i32 s49, s17, 5
	s_mul_i32 s50, s17, 0x1400
	s_lshl_b32 s51, s17, 10
	v_mov_b32_e32 v113, 0x1000
	v_lshlrev_b32_e32 v114, 2, v0
	s_mov_b32 s16, 0x3a800000
	v_mov_b32_e32 v102, 0x358637bd
	s_mov_b32 s52, 0x800000
	v_lshlrev_b32_e32 v115, 2, v2
	v_lshlrev_b32_e32 v116, 2, v4
	v_lshlrev_b32_e32 v117, 2, v6
	s_branch .LBB0_183

.Lp1_after_norm:
	v_readlane_b32 s4, v255, 62
	s_nop 3
	s_cmp_lg_u32 s4, 1
	s_cbranch_scc1 .LBB0_193
	s_mov_b32 s4, 2
	s_nop 0
	v_writelane_b32 v255, s4, 62
	s_load_dwordx2 s[6:7], s[8:9], 0xa8
	v_mov_b32_e32 v4, v195
	s_mul_i32 s4, s2, s89
	v_add_u32_e32 v0, s4, v4
	s_nop 0
	v_readfirstlane_b32 s18, v0
	s_waitcnt lgkmcnt(0)
	s_branch .Lp1_fold_entry

.LBB0_581:
	s_or_b64 exec, exec, s[10:11]
	s_lshl_b32 s68, s88, 3
	v_and_b32_e32 v213, 63, v212
	s_ashr_i32 s54, s55, 6
	s_andn2_b64 vcc, exec, s[8:9]
	s_mov_b64 s[0:1], -1
	s_cbranch_vccnz .LBB0_994
	s_waitcnt vmcnt(0)
	v_mul_f32_e32 v148, 0x3fb8aa3b, v148
	ds_write_b32 v144, v148 offset:256
	v_mul_f32_e32 v149, 0x3fb8aa3b, v149
	ds_write_b32 v144, v149 offset:2304
	v_mul_f32_e32 v150, 0x3fb8aa3b, v150
	ds_write_b32 v144, v150 offset:4352
	v_mul_f32_e32 v151, 0x3fb8aa3b, v151
	ds_write_b32 v144, v151 offset:6400
	v_mul_f32_e32 v152, 0x3fb8aa3b, v152
	ds_write_b32 v144, v152 offset:8448
	v_mul_f32_e32 v153, 0x3fb8aa3b, v153
	ds_write_b32 v144, v153 offset:10496
	v_mul_f32_e32 v154, 0x3fb8aa3b, v154
	ds_write_b32 v144, v154 offset:12544
	v_mov_b32_e32 v156, 0x88
	v_cmp_gt_u32_e64 s[16:17], v156, v212
	s_and_saveexec_b64 s[10:11], s[16:17]
	v_mul_f32_e32 v155, 0x3fb8aa3b, v155
	ds_write_b32 v144, v155 offset:14592
	s_mov_b64 exec, s[10:11]
	s_waitcnt vmcnt(0) lgkmcnt(0)
	s_barrier
	v_readlane_b32 s0, v254, 37
	v_readlane_b32 s1, v254, 38
	s_andn2_b64 vcc, exec, s[0:1]
	s_cbranch_vccnz .LBB0_993
	v_ashrrev_i32_e32 v134, 3, v212
	v_ashrrev_i32_e32 v135, 31, v134
	v_and_b32_e32 v2, 7, v212
	v_lshlrev_b64 v[0:1], 10, v[134:135]
	s_add_u32 s20, s46, 0x5bfe000
	s_movk_i32 s0, 0x90
	v_lshlrev_b32_e32 v192, 4, v2
	v_lshl_add_u64 v[0:1], s[46:47], 0, v[0:1]
	s_addc_u32 s21, s47, 0
	v_mul_lo_u32 v5, v134, s0
	v_lshl_add_u64 v[0:1], v[0:1], 0, v[192:193]
	s_mov_b64 s[0:1], 0x67fe000
	v_lshrrev_b32_e32 v4, 5, v213
	v_lshl_add_u64 v[136:137], v[0:1], 0, s[0:1]
	s_mov_b64 s[0:1], 0x73fe000
	s_add_u32 s36, s46, 0x8bfe000
	v_and_b32_e32 v3, 31, v212
	v_lshlrev_b32_e32 v132, 3, v4
	v_lshl_add_u64 v[138:139], v[0:1], 0, s[0:1]
	v_lshlrev_b32_e32 v237, 4, v4
	v_lshlrev_b32_e32 v140, 2, v4
	v_lshrrev_b32_e32 v0, 2, v212
	v_and_b32_e32 v1, 16, v212
	v_lshlrev_b32_e32 v4, 2, v213
	s_addc_u32 s37, s47, 0
	s_bfe_u32 s4, s55, 0x10006
	v_lshl_or_b32 v133, s54, 5, v3
	v_and_or_b32 v0, v0, 3, v140
	v_and_or_b32 v1, v4, 12, v1
	v_mul_u32_u24_e32 v239, 0x90, v3
	v_lshl_or_b32 v3, s4, 5, v3
	v_lshlrev_b32_e32 v238, 1, v1
	v_or_b32_e32 v1, 32, v213
	v_mul_u32_u24_e32 v241, 0x90, v0
	v_sub_u32_e64 v0, v3, 8 clamp
	v_mul_u32_u24_e32 v240, 0x90, v1
	v_min_u32_e32 v4, 48, v0
	v_lshlrev_b64 v[0:1], 7, v[134:135]
	v_lshl_add_u64 v[0:1], s[46:47], 0, v[0:1]
	v_lshl_add_u64 v[0:1], v[0:1], 0, v[192:193]
	s_mov_b64 s[0:1], 0x35fe000
	s_ashr_i32 s62, s55, 7
	v_lshl_add_u64 v[142:143], v[0:1], 0, s[0:1]
	s_mov_b64 s[0:1], 0x37fe000
	v_lshl_add_u64 v[144:145], v[0:1], 0, s[0:1]
	s_cmp_eq_u32 s4, 0
	v_sub_u32_e32 v0, v140, v3
	v_lshlrev_b32_e32 v2, 3, v2
	s_cselect_b64 s[50:51], -1, 0
	s_bitcmp1_b32 s55, 6
	v_add_u32_e32 v243, 15, v0
	v_add_u32_e32 v0, 0, v238
	s_mul_i32 s0, s62, 0xffffff84
	v_add3_u32 v141, v5, v192, 0
	v_or_b32_e32 v242, 0x1000, v3
	s_cselect_b64 s[52:53], -1, 0
	v_sub_u32_e32 v135, v4, v140
	v_add_u32_e32 v244, 0, v237
	s_add_i32 s63, s0, 0
	v_add_u32_e32 v245, v0, v241
	v_lshlrev_b32_e32 v192, 1, v2
	v_readlane_b32 s64, v255, 27
	s_mov_b32 s65, s2
	s_branch .LBB0_587

.LBB0_1001:
	s_add_u32 s50, s46, 0x67fe000
	s_addc_u32 s51, s47, 0
	s_movk_i32 s4, 0x90
	v_readlane_b32 s38, v254, 43
	s_add_u32 s36, s46, 0x73fe000
	v_mul_lo_u32 v1, v132, s4
	v_readlane_b32 s39, v254, 44
	s_addc_u32 s37, s47, 0
	v_add3_u32 v207, v1, v110, 0
	s_mov_b64 s[10:11], -1
	s_andn2_b64 vcc, exec, s[38:39]
	v_lshlrev_b32_e32 v206, 2, v69
	s_barrier
	s_waitcnt vmcnt(5)
	ds_write_b128 v207, v[90:93] offset:15360
	s_waitcnt vmcnt(4)
	ds_write_b128 v207, v[98:101] offset:24576
	v_mul_f32_e32 v148, 0x3fb8aa3b, v148
	ds_write_b32 v144, v148 offset:256
	v_mul_f32_e32 v149, 0x3fb8aa3b, v149
	ds_write_b32 v144, v149 offset:2304
	v_mul_f32_e32 v150, 0x3fb8aa3b, v150
	ds_write_b32 v144, v150 offset:4352
	v_mul_f32_e32 v151, 0x3fb8aa3b, v151
	ds_write_b32 v144, v151 offset:6400
	v_mul_f32_e32 v152, 0x3fb8aa3b, v152
	ds_write_b32 v144, v152 offset:8448
	v_mul_f32_e32 v153, 0x3fb8aa3b, v153
	ds_write_b32 v144, v153 offset:10496
	v_mul_f32_e32 v154, 0x3fb8aa3b, v154
	ds_write_b32 v144, v154 offset:12544
	v_mov_b32_e32 v156, 0x88
	v_cmp_gt_u32_e64 s[42:43], v156, v212
	s_and_saveexec_b64 s[44:45], s[42:43]
	v_mul_f32_e32 v155, 0x3fb8aa3b, v155
	ds_write_b32 v144, v155 offset:14592
	s_mov_b64 exec, s[44:45]
	s_waitcnt lgkmcnt(0)
	s_barrier
	s_cbranch_vccnz .LBB0_1003
	v_lshlrev_b32_e32 v192, 2, v69
	s_mov_b64 s[10:11], 0
